# moba-loop-tiles-seed-accumulators-with-minus-m-no-subs
# speedup vs baseline: 1.0439x; 1.0044x over previous
.LBB0_74:
	v_add_u32_e32 v169, s9, v148
	v_add_u32_e32 v183, v169, v149
	v_add_u32_e32 v184, v169, v150
	v_add_u32_e32 v185, v169, v151
	v_add_u32_e32 v186, v169, v152
	ds_read_b128 v[170:173], v183
	ds_read_b128 v[174:177], v183 offset:8192
	ds_read_b128 v[178:181], v184
	ds_read_b128 v[188:191], v184 offset:8192
	ds_read_b128 v[192:195], v185
	ds_read_b128 v[198:201], v185 offset:8192
	ds_read_b128 v[202:205], v186
	s_add_i32 s10, s6, 0x80
	v_cmp_gt_i32_e32 vcc, s10, v167
	s_and_b64 s[10:11], s[36:37], vcc
	v_cmp_lt_i32_e64 s[40:41], -1, v140
	v_xor_b32_e32 v223, 0x80000000, v142
	s_nop 0
	v_cndmask_b32_e64 v222, v235, v223, s[40:41]
	v_cndmask_b32_e64 v222, v222, v223, s[36:37]
	v_mov_b32_e32 v206, v222
	v_mov_b32_e32 v207, v222
	v_mov_b32_e32 v208, v222
	v_mov_b32_e32 v209, v222
	v_mov_b32_e32 v210, v222
	v_mov_b32_e32 v211, v222
	v_mov_b32_e32 v212, v222
	v_mov_b32_e32 v213, v222
	v_mov_b32_e32 v214, v222
	v_mov_b32_e32 v215, v222
	v_mov_b32_e32 v216, v222
	v_mov_b32_e32 v217, v222
	v_mov_b32_e32 v218, v222
	v_mov_b32_e32 v219, v222
	v_mov_b32_e32 v220, v222
	v_mov_b32_e32 v221, v222
	v_add_u32_e32 v187, v169, v153
	v_add_u32_e32 v222, v169, v154
	v_add_u32_e32 v223, v169, v155
	v_add_u32_e32 v169, v169, v156
	s_waitcnt lgkmcnt(6)
	v_mfma_f32_32x32x16_bf16 v[80:95], v[170:173], v[98:101], v[206:221]
	ds_read_b128 v[170:173], v186 offset:8192
	v_add_u32_e32 v183, s9, v159
	v_add3_u32 v183, v183, v160, v157
	v_add_u32_e32 v184, v183, v161
	v_add_u32_e32 v185, v183, v162
	v_add_u32_e32 v186, v183, v163
	v_add_u32_e32 v183, v183, v158
	s_waitcnt lgkmcnt(6)
	v_mfma_f32_32x32x16_bf16 v[64:79], v[174:177], v[98:101], v[206:221]
	ds_read_b128 v[174:177], v187
	s_waitcnt lgkmcnt(6)
	v_mfma_f32_32x32x16_bf16 v[80:95], v[178:181], v[102:105], v[80:95]
	ds_read_b128 v[178:181], v187 offset:8192
	s_waitcnt lgkmcnt(6)
	v_mfma_f32_32x32x16_bf16 v[64:79], v[188:191], v[102:105], v[64:79]
	ds_read_b128 v[188:191], v222
	s_waitcnt lgkmcnt(6)
	v_mfma_f32_32x32x16_bf16 v[80:95], v[192:195], v[106:109], v[80:95]
	ds_read_b128 v[192:195], v222 offset:8192
	s_waitcnt lgkmcnt(6)
	v_mfma_f32_32x32x16_bf16 v[64:79], v[198:201], v[106:109], v[64:79]
	ds_read_b128 v[198:201], v223
	s_waitcnt lgkmcnt(6)
	v_mfma_f32_32x32x16_bf16 v[80:95], v[202:205], v[110:113], v[80:95]
	ds_read_b128 v[202:205], v223 offset:8192
	s_waitcnt lgkmcnt(6)
	v_mfma_f32_32x32x16_bf16 v[64:79], v[170:173], v[110:113], v[64:79]
	ds_read_b128 v[170:173], v169
	s_waitcnt lgkmcnt(6)
	v_mfma_f32_32x32x16_bf16 v[80:95], v[174:177], v[114:117], v[80:95]
	ds_read_b128 v[174:177], v169 offset:8192
	s_waitcnt lgkmcnt(6)
	v_mfma_f32_32x32x16_bf16 v[64:79], v[178:181], v[114:117], v[64:79]
	s_waitcnt lgkmcnt(5)
	v_mfma_f32_32x32x16_bf16 v[80:95], v[188:191], v[118:121], v[80:95]
	ds_read_b64_tr_b16 v[188:189], v183 offset:16384
	ds_read_b64_tr_b16 v[190:191], v183 offset:18432
	s_waitcnt lgkmcnt(6)
	v_mfma_f32_32x32x16_bf16 v[64:79], v[192:195], v[118:121], v[64:79]
	ds_read_b64_tr_b16 v[192:193], v184 offset:16384
	ds_read_b64_tr_b16 v[194:195], v184 offset:18432
	s_waitcnt lgkmcnt(7)
	v_mfma_f32_32x32x16_bf16 v[80:95], v[198:201], v[122:125], v[80:95]
	ds_read_b64_tr_b16 v[198:199], v185 offset:16384
	ds_read_b64_tr_b16 v[200:201], v185 offset:18432
	s_waitcnt lgkmcnt(8)
	v_mfma_f32_32x32x16_bf16 v[64:79], v[202:205], v[122:125], v[64:79]
	ds_read_b64_tr_b16 v[202:203], v186 offset:16384
	ds_read_b64_tr_b16 v[204:205], v186 offset:18432
	s_waitcnt lgkmcnt(9)
	v_mfma_f32_32x32x16_bf16 v[80:95], v[170:173], v[126:129], v[80:95]
	s_waitcnt lgkmcnt(8)
	v_mfma_f32_32x32x16_bf16 v[64:79], v[174:177], v[126:129], v[64:79]
	s_and_saveexec_b64 s[40:41], s[10:11]
	s_cbranch_execz .LBB0_76
	v_sub_u32_e32 v169, v140, v146
	v_cmp_lt_i32_e32 vcc, -1, v169
	s_nop 4
	v_cndmask_b32_e32 v80, v235, v80, vcc
	v_cmp_lt_i32_e32 vcc, 0, v169
	s_nop 1
	v_cndmask_b32_e32 v81, v235, v81, vcc
	v_cmp_lt_i32_e32 vcc, 1, v169
	s_nop 1
	v_cndmask_b32_e32 v82, v235, v82, vcc
	v_cmp_lt_i32_e32 vcc, 2, v169
	s_nop 1
	v_cndmask_b32_e32 v83, v235, v83, vcc
	v_cmp_lt_i32_e32 vcc, 7, v169
	s_nop 1
	v_cndmask_b32_e32 v84, v235, v84, vcc
	v_cmp_lt_i32_e32 vcc, 8, v169
	s_nop 1
	v_cndmask_b32_e32 v85, v235, v85, vcc
	v_cmp_lt_i32_e32 vcc, 9, v169
	s_nop 1
	v_cndmask_b32_e32 v86, v235, v86, vcc
	v_cmp_lt_i32_e32 vcc, 10, v169
	s_nop 1
	v_cndmask_b32_e32 v87, v235, v87, vcc
	v_cmp_lt_i32_e32 vcc, 15, v169
	s_nop 1
	v_cndmask_b32_e32 v88, v235, v88, vcc
	v_cmp_lt_i32_e32 vcc, 16, v169
	s_nop 1
	v_cndmask_b32_e32 v89, v235, v89, vcc
	v_cmp_lt_i32_e32 vcc, 17, v169
	s_nop 1
	v_cndmask_b32_e32 v90, v235, v90, vcc
	v_cmp_lt_i32_e32 vcc, 18, v169
	s_nop 1
	v_cndmask_b32_e32 v91, v235, v91, vcc
	v_cmp_lt_i32_e32 vcc, 23, v169
	s_nop 1
	v_cndmask_b32_e32 v92, v235, v92, vcc
	v_cmp_lt_i32_e32 vcc, 24, v169
	s_nop 1
	v_cndmask_b32_e32 v93, v235, v93, vcc
	v_cmp_lt_i32_e32 vcc, 25, v169
	s_nop 1
	v_cndmask_b32_e32 v94, v235, v94, vcc
	v_cmp_lt_i32_e32 vcc, 26, v169
	s_nop 1
	v_cndmask_b32_e32 v95, v235, v95, vcc
	v_cmp_lt_i32_e32 vcc, 31, v169
	s_nop 1
	v_cndmask_b32_e32 v64, v235, v64, vcc
	v_cmp_lt_i32_e32 vcc, 32, v169
	s_nop 1
	v_cndmask_b32_e32 v65, v235, v65, vcc
	v_cmp_lt_i32_e32 vcc, 33, v169
	s_nop 1
	v_cndmask_b32_e32 v66, v235, v66, vcc
	v_cmp_lt_i32_e32 vcc, 34, v169
	s_nop 1
	v_cndmask_b32_e32 v67, v235, v67, vcc
	v_cmp_lt_i32_e32 vcc, 39, v169
	s_nop 1
	v_cndmask_b32_e32 v68, v235, v68, vcc
	v_cmp_lt_i32_e32 vcc, 40, v169
	s_nop 1
	v_cndmask_b32_e32 v69, v235, v69, vcc
	v_cmp_lt_i32_e32 vcc, 41, v169
	s_nop 1
	v_cndmask_b32_e32 v70, v235, v70, vcc
	v_cmp_lt_i32_e32 vcc, 42, v169
	s_nop 1
	v_cndmask_b32_e32 v71, v235, v71, vcc
	v_cmp_lt_i32_e32 vcc, 47, v169
	s_nop 1
	v_cndmask_b32_e32 v72, v235, v72, vcc
	v_cmp_lt_i32_e32 vcc, 48, v169
	s_nop 1
	v_cndmask_b32_e32 v73, v235, v73, vcc
	v_cmp_lt_i32_e32 vcc, 49, v169
	s_nop 1
	v_cndmask_b32_e32 v74, v235, v74, vcc
	v_cmp_lt_i32_e32 vcc, 50, v169
	s_nop 1
	v_cndmask_b32_e32 v75, v235, v75, vcc
	v_cmp_lt_i32_e32 vcc, 55, v169
	s_nop 1
	v_cndmask_b32_e32 v76, v235, v76, vcc
	v_cmp_lt_i32_e32 vcc, 56, v169
	s_nop 1
	v_cndmask_b32_e32 v77, v235, v77, vcc
	v_cmp_lt_i32_e32 vcc, 57, v169
	s_nop 1
	v_cndmask_b32_e32 v78, v235, v78, vcc
	v_cmp_lt_i32_e32 vcc, 58, v169
	s_nop 1
	v_cndmask_b32_e32 v79, v235, v79, vcc
.LBB0_76:
	s_or_b64 exec, exec, s[40:41]
	s_nop 7
.LBB0_78:
	v_exp_f32_e32 v171, v80
	v_exp_f32_e32 v81, v81
	v_exp_f32_e32 v173, v69
	v_exp_f32_e32 v82, v82
	v_exp_f32_e32 v174, v70
	v_exp_f32_e32 v83, v83
	v_exp_f32_e32 v71, v71
	v_add_f32_e32 v80, 0, v171
	v_exp_f32_e32 v84, v84
	v_exp_f32_e32 v175, v72
	v_add_f32_e32 v80, v81, v80
	v_exp_f32_e32 v85, v85
	v_exp_f32_e32 v176, v73
	v_add_f32_e32 v80, v82, v80
	v_exp_f32_e32 v86, v86
	v_exp_f32_e32 v87, v87
	v_exp_f32_e32 v177, v74
	v_add_f32_e32 v80, v83, v80
	v_exp_f32_e32 v178, v75
	v_add_f32_e32 v80, v84, v80
	v_exp_f32_e32 v179, v76
	v_cvt_pk_bf16_f32 v76, v171, v81
	v_add_f32_e32 v80, v85, v80
	v_exp_f32_e32 v180, v77
	v_add_f32_e32 v80, v86, v80
	v_exp_f32_e32 v181, v78
	v_mov_b32_e32 v69, v79
	v_cvt_pk_bf16_f32 v79, v86, v87
	v_cvt_pk_bf16_f32 v77, v82, v83
	v_cvt_pk_bf16_f32 v78, v84, v85
	v_add_f32_e32 v80, v87, v80
	v_exp_f32_e32 v88, v88
	v_exp_f32_e32 v89, v89
	s_waitcnt lgkmcnt(6)
	v_mfma_f32_32x32x16_bf16 v[48:63], v[188:191], v[76:79], v[48:63]
	ds_read_b64_tr_b16 v[188:189], v183 offset:20480
	ds_read_b64_tr_b16 v[190:191], v183 offset:22528
	v_add_f32_e32 v80, v88, v80
	v_cvt_pk_bf16_f32 v72, v88, v89
	v_exp_f32_e32 v90, v90
	s_waitcnt lgkmcnt(6)
	v_mfma_f32_32x32x16_bf16 v[32:47], v[192:195], v[76:79], v[32:47]
	ds_read_b64_tr_b16 v[192:193], v184 offset:20480
	ds_read_b64_tr_b16 v[194:195], v184 offset:22528
	v_exp_f32_e32 v91, v91
	s_waitcnt lgkmcnt(6)
	v_mfma_f32_32x32x16_bf16 v[16:31], v[198:201], v[76:79], v[16:31]
	ds_read_b64_tr_b16 v[198:199], v185 offset:20480
	ds_read_b64_tr_b16 v[200:201], v185 offset:22528
	v_exp_f32_e32 v92, v92
	v_exp_f32_e32 v93, v93
	v_exp_f32_e32 v94, v94
	v_exp_f32_e32 v95, v95
	v_add_f32_e32 v80, v89, v80
	v_add_f32_e32 v80, v90, v80
	s_waitcnt lgkmcnt(6)
	v_mfma_f32_32x32x16_bf16 v[0:15], v[202:205], v[76:79], v[0:15]
	ds_read_b64_tr_b16 v[202:203], v186 offset:20480
	ds_read_b64_tr_b16 v[204:205], v186 offset:22528
	v_add_f32_e32 v80, v91, v80
	v_cvt_pk_bf16_f32 v73, v90, v91
	v_cvt_pk_bf16_f32 v74, v92, v93
	v_cvt_pk_bf16_f32 v75, v94, v95
	v_add_f32_e32 v80, v92, v80
	v_exp_f32_e32 v64, v64
	s_waitcnt lgkmcnt(6)
	v_mfma_f32_32x32x16_bf16 v[48:63], v[188:191], v[72:75], v[48:63]
	ds_read_b64_tr_b16 v[188:189], v183 offset:24576
	ds_read_b64_tr_b16 v[190:191], v183 offset:26624
	v_add_f32_e32 v80, v93, v80
	v_exp_f32_e32 v65, v65
	v_add_f32_e32 v80, v94, v80
	v_exp_f32_e32 v66, v66
	v_add_f32_e32 v80, v95, v80
	v_exp_f32_e32 v67, v67
	v_add_f32_e32 v80, v64, v80
	v_exp_f32_e32 v172, v68
	v_add_f32_e32 v80, v65, v80
	s_waitcnt lgkmcnt(6)
	v_mfma_f32_32x32x16_bf16 v[32:47], v[192:195], v[72:75], v[32:47]
	ds_read_b64_tr_b16 v[192:193], v184 offset:24576
	ds_read_b64_tr_b16 v[194:195], v184 offset:26624
	v_add_f32_e32 v80, v66, v80
	v_add_f32_e32 v80, v67, v80
	v_add_f32_e32 v68, v172, v80
	v_add_f32_e32 v68, v173, v68
	v_add_f32_e32 v68, v174, v68
	v_add_f32_e32 v68, v71, v68
	s_waitcnt lgkmcnt(6)
	v_mfma_f32_32x32x16_bf16 v[16:31], v[198:201], v[72:75], v[16:31]
	ds_read_b64_tr_b16 v[198:199], v185 offset:24576
	ds_read_b64_tr_b16 v[200:201], v185 offset:26624
	v_add_f32_e32 v68, v175, v68
	v_add_f32_e32 v68, v176, v68
	v_add_f32_e32 v68, v177, v68
	v_add_f32_e32 v68, v178, v68
	v_exp_f32_e32 v182, v69
	v_add_f32_e32 v68, v179, v68
	s_waitcnt lgkmcnt(6)
	v_mfma_f32_32x32x16_bf16 v[0:15], v[202:205], v[72:75], v[0:15]
	ds_read_b64_tr_b16 v[202:203], v186 offset:24576
	ds_read_b64_tr_b16 v[204:205], v186 offset:26624
	v_add_f32_e32 v68, v180, v68
	v_add_f32_e32 v68, v181, v68
	v_add_f32_e32 v80, v182, v68
	v_cvt_pk_bf16_f32 v68, v64, v65
	v_cvt_pk_bf16_f32 v69, v66, v67
	v_cvt_pk_bf16_f32 v70, v172, v173
	v_cvt_pk_bf16_f32 v71, v174, v71
	v_cvt_pk_bf16_f32 v64, v175, v176
	v_cvt_pk_bf16_f32 v65, v177, v178
	s_waitcnt lgkmcnt(6)
	v_mfma_f32_32x32x16_bf16 v[48:63], v[188:191], v[68:71], v[48:63]
	ds_read_b64_tr_b16 v[188:189], v183 offset:28672
	ds_read_b64_tr_b16 v[190:191], v183 offset:30720
	v_cvt_pk_bf16_f32 v66, v179, v180
	v_cvt_pk_bf16_f32 v67, v181, v182
	v_add_f32_e32 v80, v168, v80
	v_mov_b32_e32 v168, v80
	s_waitcnt lgkmcnt(6)
	v_mfma_f32_32x32x16_bf16 v[32:47], v[192:195], v[68:71], v[32:47]
	ds_read_b64_tr_b16 v[192:193], v184 offset:28672
	ds_read_b64_tr_b16 v[194:195], v184 offset:30720
	s_waitcnt lgkmcnt(6)
	v_mfma_f32_32x32x16_bf16 v[16:31], v[198:201], v[68:71], v[16:31]
	ds_read_b64_tr_b16 v[198:199], v185 offset:28672
	ds_read_b64_tr_b16 v[200:201], v185 offset:30720
	s_waitcnt lgkmcnt(6)
	v_mfma_f32_32x32x16_bf16 v[0:15], v[202:205], v[68:71], v[0:15]
	ds_read_b64_tr_b16 v[202:203], v186 offset:28672
	ds_read_b64_tr_b16 v[204:205], v186 offset:30720
	s_waitcnt lgkmcnt(6)
	v_mfma_f32_32x32x16_bf16 v[48:63], v[188:191], v[64:67], v[48:63]
	s_waitcnt lgkmcnt(4)
	v_mfma_f32_32x32x16_bf16 v[32:47], v[192:195], v[64:67], v[32:47]
	s_waitcnt lgkmcnt(2)
	v_mfma_f32_32x32x16_bf16 v[16:31], v[198:201], v[64:67], v[16:31]
	s_waitcnt lgkmcnt(0)
	v_mfma_f32_32x32x16_bf16 v[0:15], v[202:205], v[64:67], v[0:15]

.LBB0_84:
	v_add_u32_e32 v140, s9, v148
	v_add_u32_e32 v183, v140, v149
	v_add_u32_e32 v184, v140, v150
	v_add_u32_e32 v185, v140, v151
	v_add_u32_e32 v186, v140, v152
	ds_read_b128 v[170:173], v183 offset:32768
	ds_read_b128 v[174:177], v183 offset:40960
	ds_read_b128 v[178:181], v184 offset:32768
	ds_read_b128 v[188:191], v184 offset:40960
	ds_read_b128 v[192:195], v185 offset:32768
	ds_read_b128 v[198:201], v185 offset:40960
	ds_read_b128 v[202:205], v186 offset:32768
	s_add_i32 s10, s6, 0xc0
	v_cmp_gt_i32_e32 vcc, s10, v167
	s_and_b64 s[10:11], s[36:37], vcc
	v_add_u32_e32 v187, v140, v153
	v_add_u32_e32 v222, v140, v154
	v_add_u32_e32 v223, v140, v155
	v_add_u32_e32 v140, v140, v156
	s_waitcnt lgkmcnt(6)
	v_mfma_f32_32x32x16_bf16 v[80:95], v[170:173], v[98:101], v[206:221]
	ds_read_b128 v[170:173], v186 offset:40960
	v_add_u32_e32 v183, s9, v159
	v_add3_u32 v183, v183, v160, v157
	v_add_u32_e32 v184, v183, v161
	v_add_u32_e32 v185, v183, v162
	v_add_u32_e32 v186, v183, v163
	v_add_u32_e32 v183, v183, v158
	s_waitcnt lgkmcnt(6)
	v_mfma_f32_32x32x16_bf16 v[64:79], v[174:177], v[98:101], v[206:221]
	ds_read_b128 v[174:177], v187 offset:32768
	s_waitcnt lgkmcnt(6)
	v_mfma_f32_32x32x16_bf16 v[80:95], v[178:181], v[102:105], v[80:95]
	ds_read_b128 v[178:181], v187 offset:40960
	s_waitcnt lgkmcnt(6)
	v_mfma_f32_32x32x16_bf16 v[64:79], v[188:191], v[102:105], v[64:79]
	ds_read_b128 v[188:191], v222 offset:32768
	s_waitcnt lgkmcnt(6)
	v_mfma_f32_32x32x16_bf16 v[80:95], v[192:195], v[106:109], v[80:95]
	ds_read_b128 v[192:195], v222 offset:40960
	s_waitcnt lgkmcnt(6)
	v_mfma_f32_32x32x16_bf16 v[64:79], v[198:201], v[106:109], v[64:79]
	ds_read_b128 v[198:201], v223 offset:32768
	s_waitcnt lgkmcnt(6)
	v_mfma_f32_32x32x16_bf16 v[80:95], v[202:205], v[110:113], v[80:95]
	ds_read_b128 v[202:205], v223 offset:40960
	s_waitcnt lgkmcnt(6)
	v_mfma_f32_32x32x16_bf16 v[64:79], v[170:173], v[110:113], v[64:79]
	ds_read_b128 v[170:173], v140 offset:32768
	s_waitcnt lgkmcnt(6)
	v_mfma_f32_32x32x16_bf16 v[80:95], v[174:177], v[114:117], v[80:95]
	ds_read_b128 v[174:177], v140 offset:40960
	s_waitcnt lgkmcnt(6)
	v_mfma_f32_32x32x16_bf16 v[64:79], v[178:181], v[114:117], v[64:79]
	s_waitcnt lgkmcnt(5)
	v_mfma_f32_32x32x16_bf16 v[80:95], v[188:191], v[118:121], v[80:95]
	ds_read_b64_tr_b16 v[188:189], v183 offset:49152
	ds_read_b64_tr_b16 v[190:191], v183 offset:51200
	s_waitcnt lgkmcnt(6)
	v_mfma_f32_32x32x16_bf16 v[64:79], v[192:195], v[118:121], v[64:79]
	ds_read_b64_tr_b16 v[192:193], v184 offset:49152
	ds_read_b64_tr_b16 v[194:195], v184 offset:51200
	s_waitcnt lgkmcnt(7)
	v_mfma_f32_32x32x16_bf16 v[80:95], v[198:201], v[122:125], v[80:95]
	ds_read_b64_tr_b16 v[198:199], v185 offset:49152
	ds_read_b64_tr_b16 v[200:201], v185 offset:51200
	s_waitcnt lgkmcnt(8)
	v_mfma_f32_32x32x16_bf16 v[64:79], v[202:205], v[122:125], v[64:79]
	ds_read_b64_tr_b16 v[202:203], v186 offset:49152
	ds_read_b64_tr_b16 v[204:205], v186 offset:51200
	s_waitcnt lgkmcnt(9)
	v_mfma_f32_32x32x16_bf16 v[80:95], v[170:173], v[126:129], v[80:95]
	s_waitcnt lgkmcnt(8)
	v_mfma_f32_32x32x16_bf16 v[64:79], v[174:177], v[126:129], v[64:79]
	s_and_saveexec_b64 s[38:39], s[10:11]
	s_cbranch_execz .LBB0_86
	v_sub_u32_e32 v140, v133, v146
	v_cmp_lt_i32_e32 vcc, -1, v140
	s_nop 4
	v_cndmask_b32_e32 v80, v235, v80, vcc
	v_cmp_lt_i32_e32 vcc, 0, v140
	s_nop 1
	v_cndmask_b32_e32 v81, v235, v81, vcc
	v_cmp_lt_i32_e32 vcc, 1, v140
	s_nop 1
	v_cndmask_b32_e32 v82, v235, v82, vcc
	v_cmp_lt_i32_e32 vcc, 2, v140
	s_nop 1
	v_cndmask_b32_e32 v83, v235, v83, vcc
	v_cmp_lt_i32_e32 vcc, 7, v140
	s_nop 1
	v_cndmask_b32_e32 v84, v235, v84, vcc
	v_cmp_lt_i32_e32 vcc, 8, v140
	s_nop 1
	v_cndmask_b32_e32 v85, v235, v85, vcc
	v_cmp_lt_i32_e32 vcc, 9, v140
	s_nop 1
	v_cndmask_b32_e32 v86, v235, v86, vcc
	v_cmp_lt_i32_e32 vcc, 10, v140
	s_nop 1
	v_cndmask_b32_e32 v87, v235, v87, vcc
	v_cmp_lt_i32_e32 vcc, 15, v140
	s_nop 1
	v_cndmask_b32_e32 v88, v235, v88, vcc
	v_cmp_lt_i32_e32 vcc, 16, v140
	s_nop 1
	v_cndmask_b32_e32 v89, v235, v89, vcc
	v_cmp_lt_i32_e32 vcc, 17, v140
	s_nop 1
	v_cndmask_b32_e32 v90, v235, v90, vcc
	v_cmp_lt_i32_e32 vcc, 18, v140
	s_nop 1
	v_cndmask_b32_e32 v91, v235, v91, vcc
	v_cmp_lt_i32_e32 vcc, 23, v140
	s_nop 1
	v_cndmask_b32_e32 v92, v235, v92, vcc
	v_cmp_lt_i32_e32 vcc, 24, v140
	s_nop 1
	v_cndmask_b32_e32 v93, v235, v93, vcc
	v_cmp_lt_i32_e32 vcc, 25, v140
	s_nop 1
	v_cndmask_b32_e32 v94, v235, v94, vcc
	v_cmp_lt_i32_e32 vcc, 26, v140
	s_nop 1
	v_cndmask_b32_e32 v95, v235, v95, vcc
	v_cmp_lt_i32_e32 vcc, 31, v140
	s_nop 1
	v_cndmask_b32_e32 v64, v235, v64, vcc
	v_cmp_lt_i32_e32 vcc, 32, v140
	s_nop 1
	v_cndmask_b32_e32 v65, v235, v65, vcc
	v_cmp_lt_i32_e32 vcc, 33, v140
	s_nop 1
	v_cndmask_b32_e32 v66, v235, v66, vcc
	v_cmp_lt_i32_e32 vcc, 34, v140
	s_nop 1
	v_cndmask_b32_e32 v67, v235, v67, vcc
	v_cmp_lt_i32_e32 vcc, 39, v140
	s_nop 1
	v_cndmask_b32_e32 v68, v235, v68, vcc
	v_cmp_lt_i32_e32 vcc, 40, v140
	s_nop 1
	v_cndmask_b32_e32 v69, v235, v69, vcc
	v_cmp_lt_i32_e32 vcc, 41, v140
	s_nop 1
	v_cndmask_b32_e32 v70, v235, v70, vcc
	v_cmp_lt_i32_e32 vcc, 42, v140
	s_nop 1
	v_cndmask_b32_e32 v71, v235, v71, vcc
	v_cmp_lt_i32_e32 vcc, 47, v140
	s_nop 1
	v_cndmask_b32_e32 v72, v235, v72, vcc
	v_cmp_lt_i32_e32 vcc, 48, v140
	s_nop 1
	v_cndmask_b32_e32 v73, v235, v73, vcc
	v_cmp_lt_i32_e32 vcc, 49, v140
	s_nop 1
	v_cndmask_b32_e32 v74, v235, v74, vcc
	v_cmp_lt_i32_e32 vcc, 50, v140
	s_nop 1
	v_cndmask_b32_e32 v75, v235, v75, vcc
	v_cmp_lt_i32_e32 vcc, 55, v140
	s_nop 1
	v_cndmask_b32_e32 v76, v235, v76, vcc
	v_cmp_lt_i32_e32 vcc, 56, v140
	s_nop 1
	v_cndmask_b32_e32 v77, v235, v77, vcc
	v_cmp_lt_i32_e32 vcc, 57, v140
	s_nop 1
	v_cndmask_b32_e32 v78, v235, v78, vcc
	v_cmp_lt_i32_e32 vcc, 58, v140
	s_nop 1
	v_cndmask_b32_e32 v79, v235, v79, vcc
.LBB0_86:
	s_or_b64 exec, exec, s[38:39]
	s_nop 7
.LBB0_88:
	v_exp_f32_e32 v170, v80
	v_exp_f32_e32 v81, v81
	v_exp_f32_e32 v172, v69
	v_exp_f32_e32 v82, v82
	v_exp_f32_e32 v173, v70
	v_exp_f32_e32 v83, v83
	v_exp_f32_e32 v71, v71
	v_add_f32_e32 v80, 0, v170
	v_exp_f32_e32 v84, v84
	v_exp_f32_e32 v174, v72
	v_add_f32_e32 v80, v81, v80
	v_exp_f32_e32 v85, v85
	v_exp_f32_e32 v175, v73
	v_add_f32_e32 v80, v82, v80
	v_exp_f32_e32 v86, v86
	v_exp_f32_e32 v87, v87
	v_exp_f32_e32 v176, v74
	v_add_f32_e32 v80, v83, v80
	v_exp_f32_e32 v177, v75
	v_add_f32_e32 v80, v84, v80
	v_exp_f32_e32 v178, v76
	v_cvt_pk_bf16_f32 v76, v170, v81
	v_add_f32_e32 v80, v85, v80
	v_exp_f32_e32 v179, v77
	v_add_f32_e32 v80, v86, v80
	v_exp_f32_e32 v180, v78
	v_mov_b32_e32 v69, v79
	v_cvt_pk_bf16_f32 v79, v86, v87
	v_cvt_pk_bf16_f32 v77, v82, v83
	v_cvt_pk_bf16_f32 v78, v84, v85
	v_add_f32_e32 v80, v87, v80
	v_exp_f32_e32 v88, v88
	v_exp_f32_e32 v89, v89
	s_waitcnt lgkmcnt(6)
	v_mfma_f32_32x32x16_bf16 v[48:63], v[188:191], v[76:79], v[48:63]
	ds_read_b64_tr_b16 v[188:189], v183 offset:53248
	ds_read_b64_tr_b16 v[190:191], v183 offset:55296
	v_add_f32_e32 v80, v88, v80
	v_cvt_pk_bf16_f32 v72, v88, v89
	v_exp_f32_e32 v90, v90
	s_waitcnt lgkmcnt(6)
	v_mfma_f32_32x32x16_bf16 v[32:47], v[192:195], v[76:79], v[32:47]
	ds_read_b64_tr_b16 v[192:193], v184 offset:53248
	ds_read_b64_tr_b16 v[194:195], v184 offset:55296
	v_exp_f32_e32 v91, v91
	s_waitcnt lgkmcnt(6)
	v_mfma_f32_32x32x16_bf16 v[16:31], v[198:201], v[76:79], v[16:31]
	ds_read_b64_tr_b16 v[198:199], v185 offset:53248
	ds_read_b64_tr_b16 v[200:201], v185 offset:55296
	v_exp_f32_e32 v92, v92
	v_exp_f32_e32 v93, v93
	v_exp_f32_e32 v94, v94
	v_exp_f32_e32 v95, v95
	v_add_f32_e32 v80, v89, v80
	v_add_f32_e32 v80, v90, v80
	s_waitcnt lgkmcnt(6)
	v_mfma_f32_32x32x16_bf16 v[0:15], v[202:205], v[76:79], v[0:15]
	ds_read_b64_tr_b16 v[202:203], v186 offset:53248
	ds_read_b64_tr_b16 v[204:205], v186 offset:55296
	v_add_f32_e32 v80, v91, v80
	v_cvt_pk_bf16_f32 v73, v90, v91
	v_cvt_pk_bf16_f32 v74, v92, v93
	v_cvt_pk_bf16_f32 v75, v94, v95
	v_add_f32_e32 v80, v92, v80
	v_exp_f32_e32 v64, v64
	s_waitcnt lgkmcnt(6)
	v_mfma_f32_32x32x16_bf16 v[48:63], v[188:191], v[72:75], v[48:63]
	ds_read_b64_tr_b16 v[188:189], v183 offset:57344
	ds_read_b64_tr_b16 v[190:191], v183 offset:59392
	v_add_f32_e32 v80, v93, v80
	v_exp_f32_e32 v65, v65
	v_add_f32_e32 v80, v94, v80
	v_exp_f32_e32 v66, v66
	v_add_f32_e32 v80, v95, v80
	v_exp_f32_e32 v67, v67
	v_add_f32_e32 v80, v64, v80
	v_exp_f32_e32 v171, v68
	v_add_f32_e32 v80, v65, v80
	s_waitcnt lgkmcnt(6)
	v_mfma_f32_32x32x16_bf16 v[32:47], v[192:195], v[72:75], v[32:47]
	ds_read_b64_tr_b16 v[192:193], v184 offset:57344
	ds_read_b64_tr_b16 v[194:195], v184 offset:59392
	v_add_f32_e32 v80, v66, v80
	v_add_f32_e32 v80, v67, v80
	v_add_f32_e32 v68, v171, v80
	v_add_f32_e32 v68, v172, v68
	v_add_f32_e32 v68, v173, v68
	v_add_f32_e32 v68, v71, v68
	s_waitcnt lgkmcnt(6)
	v_mfma_f32_32x32x16_bf16 v[16:31], v[198:201], v[72:75], v[16:31]
	ds_read_b64_tr_b16 v[198:199], v185 offset:57344
	ds_read_b64_tr_b16 v[200:201], v185 offset:59392
	v_add_f32_e32 v68, v174, v68
	v_add_f32_e32 v68, v175, v68
	v_add_f32_e32 v68, v176, v68
	v_add_f32_e32 v68, v177, v68
	v_exp_f32_e32 v181, v69
	v_add_f32_e32 v68, v178, v68
	s_waitcnt lgkmcnt(6)
	v_mfma_f32_32x32x16_bf16 v[0:15], v[202:205], v[72:75], v[0:15]
	ds_read_b64_tr_b16 v[202:203], v186 offset:57344
	ds_read_b64_tr_b16 v[204:205], v186 offset:59392
	v_add_f32_e32 v68, v179, v68
	v_add_f32_e32 v68, v180, v68
	v_add_f32_e32 v80, v181, v68
	v_cvt_pk_bf16_f32 v68, v64, v65
	v_cvt_pk_bf16_f32 v69, v66, v67
	v_cvt_pk_bf16_f32 v70, v171, v172
	v_cvt_pk_bf16_f32 v71, v173, v71
	v_cvt_pk_bf16_f32 v64, v174, v175
	v_cvt_pk_bf16_f32 v65, v176, v177
	s_waitcnt lgkmcnt(6)
	v_mfma_f32_32x32x16_bf16 v[48:63], v[188:191], v[68:71], v[48:63]
	ds_read_b64_tr_b16 v[188:189], v183 offset:61440
	ds_read_b64_tr_b16 v[190:191], v183 offset:63488
	v_cvt_pk_bf16_f32 v66, v178, v179
	v_cvt_pk_bf16_f32 v67, v180, v181
	v_add_f32_e32 v80, v168, v80
	v_mov_b32_e32 v168, v80
	s_waitcnt lgkmcnt(6)
	v_mfma_f32_32x32x16_bf16 v[32:47], v[192:195], v[68:71], v[32:47]
	ds_read_b64_tr_b16 v[192:193], v184 offset:61440
	ds_read_b64_tr_b16 v[194:195], v184 offset:63488
	s_waitcnt lgkmcnt(6)
	v_mfma_f32_32x32x16_bf16 v[16:31], v[198:201], v[68:71], v[16:31]
	ds_read_b64_tr_b16 v[198:199], v185 offset:61440
	ds_read_b64_tr_b16 v[200:201], v185 offset:63488
	s_waitcnt lgkmcnt(6)
	v_mfma_f32_32x32x16_bf16 v[0:15], v[202:205], v[68:71], v[0:15]
	ds_read_b64_tr_b16 v[202:203], v186 offset:61440
	ds_read_b64_tr_b16 v[204:205], v186 offset:63488
	s_waitcnt lgkmcnt(6)
	v_mfma_f32_32x32x16_bf16 v[48:63], v[188:191], v[64:67], v[48:63]
	s_waitcnt lgkmcnt(4)
	v_mfma_f32_32x32x16_bf16 v[32:47], v[192:195], v[64:67], v[32:47]
	s_waitcnt lgkmcnt(2)
	v_mfma_f32_32x32x16_bf16 v[16:31], v[198:201], v[64:67], v[16:31]
	s_waitcnt lgkmcnt(0)
	v_mfma_f32_32x32x16_bf16 v[0:15], v[202:205], v[64:67], v[0:15]
